# +E12 chunk chains: operand-fragment ds_reads issued 8 ahead in consumption order with counted lgkmcnt waits (was read-wait-mfma per step)
# speedup vs baseline: 1.0102x; 1.0102x over previous
; #define LAS __attribute__((address_space(3)))
; __device__ __forceinline__ float bf_lo(unsigned w) { return __uint_as_float(w << 16); }
; __device__ __forceinline__ float bf_hi(unsigned w) { return __uint_as_float(w & 0xffff0000u); }
; template <bool GD>
; __device__ __forceinline__ void chain_wg(CArgs* a, LAS unsigned char* lds, int l, int bh) {
;     ...
;         bf16x8 Sf[4];
; #pragma unroll
;         for (int ks = 0; ks < 4; ++ks) Sf[ks] = pack_frag(S[2 * ks], S[2 * ks + 1]);
;         bf16x8 Vf[2];
;         f32x4 o[4];
;         if (GD) {
;             f32x4 vn[4];
; #pragma unroll
;             for (int pr = 0; pr < 2; ++pr) { vn[2 * pr] = (f32x4){bf_lo(un[pr].x), bf_hi(un[pr].x), bf_lo(un[pr].y), bf_hi(un[pr].y)}; vn[2 * pr + 1] = (f32x4){bf_lo(un[pr].z), bf_hi(un[pr].z), bf_lo(un[pr].w), bf_hi(un[pr].w)}; }
; #pragma unroll
;             for (int tb = 0; tb < 4; ++tb)
; #pragma unroll
;                 for (int ks = 0; ks < 4; ++ks) vn[tb] = __builtin_amdgcn_mfma_f32_16x16x32_bf16(*(const LAS bf16x8*)(B + OG_WN + (tb * 4 + ks) * 1024 + lane * 16), Sf[ks], vn[tb], 0, 0, 0);
;             Vf[0] = pack_frag(vn[0], vn[1]); Vf[1] = pack_frag(vn[2], vn[3]);
;         } else {
;             Vf[0] = *(const LAS bf16x8*)(B + OP_VT + (wid * 2 + 0) * 1024 + lane * 16); Vf[1] = *(const LAS bf16x8*)(B + OP_VT + (wid * 2 + 1) * 1024 + lane * 16);
;         }
; #pragma unroll
;         for (int tb = 0; tb < 4; ++tb) { o[tb] = zero4;
; #pragma unroll
;             for (int ks = 0; ks < 4; ++ks) o[tb] = __builtin_amdgcn_mfma_f32_16x16x32_bf16(*(const LAS bf16x8*)(B + (GD ? OG_QG : OP_QG) + (tb * 4 + ks) * 1024 + lane * 16), Sf[ks], o[tb], 0, 0, 0);
; #pragma unroll
;             for (int k2 = 0; k2 < 2; ++k2) o[tb] = __builtin_amdgcn_mfma_f32_16x16x32_bf16(*(const LAS bf16x8*)(B + (GD ? OG_QK : OP_A) + (tb * 2 + k2) * 1024 + lane * 16), Vf[k2], o[tb], 0, 0, 0); }
;         const float eg = GD ? *(const LAS float*)(B + OP_MISC) : 0.f;
; #pragma unroll
;         for (int db = 0; db < 8; ++db) {
;             if (GD) S[db] = S[db] * eg; else S[db] = S[db] * *(const LAS f32x4*)(B + OP_MISC + (16 * db + 4 * fq) * 4);
; #pragma unroll
;             for (int k2 = 0; k2 < 2; ++k2) S[db] = __builtin_amdgcn_mfma_f32_16x16x32_bf16(*(const LAS bf16x8*)(B + (GD ? OG_KDT : OP_KDT) + (db * 2 + k2) * 1024 + lane * 16), Vf[k2], S[db], 0, 0, 0); }
.LBB0_1143:
	s_and_b32 s14, s19, 1
	s_mul_i32 s15, s14, 0xe400
	s_add_i32 s15, s15, 0
	s_add_i32 s16, s15, s18
	v_add_u32_e32 v68, s16, v104
	v_add_u32_e32 v116, s15, v104
	ds_read_b128 v[72:75], v68 offset:40960
	ds_read_b128 v[68:71], v68 offset:41984
	ds_read_b128 v[160:163], v116
	ds_read_b128 v[164:167], v116 offset:1024
	ds_read_b128 v[168:171], v116 offset:2048
	ds_read_b128 v[172:175], v116 offset:3072
	ds_read_b128 v[176:179], v116 offset:16384
	ds_read_b128 v[180:183], v116 offset:17408
	ds_read_b128 v[184:187], v116 offset:4096
	ds_read_b128 v[188:191], v116 offset:5120
	v_cvt_pk_bf16_f32 v88, v44, v45
	v_cvt_pk_bf16_f32 v89, v46, v47
	v_cvt_pk_bf16_f32 v90, v48, v49
	v_cvt_pk_bf16_f32 v91, v50, v51
	v_cvt_pk_bf16_f32 v100, v40, v41
	v_cvt_pk_bf16_f32 v101, v42, v43
	s_waitcnt lgkmcnt(7)
	v_mfma_f32_16x16x32_bf16 v[76:79], v[160:163], v[88:91], 0
	ds_read_b128 v[160:163], v116 offset:6144
	v_cvt_pk_bf16_f32 v102, v36, v37
	v_cvt_pk_bf16_f32 v103, v38, v39
	v_cvt_pk_bf16_f32 v96, v32, v33
	v_cvt_pk_bf16_f32 v97, v34, v35
	s_waitcnt lgkmcnt(7)
	v_mfma_f32_16x16x32_bf16 v[76:79], v[164:167], v[100:103], v[76:79]
	ds_read_b128 v[164:167], v116 offset:7168
	v_cvt_pk_bf16_f32 v98, v24, v25
	v_cvt_pk_bf16_f32 v99, v26, v27
	v_cvt_pk_bf16_f32 v92, v20, v21
	v_cvt_pk_bf16_f32 v93, v22, v23
	s_waitcnt lgkmcnt(7)
	v_mfma_f32_16x16x32_bf16 v[76:79], v[168:171], v[96:99], v[76:79]
	ds_read_b128 v[168:171], v116 offset:18432
	v_cvt_pk_bf16_f32 v94, v28, v29
	v_cvt_pk_bf16_f32 v95, v30, v31
	v_lshl_add_u32 v122, s14, 11, v113
	v_add_u32_e32 v123, s22, v122
	s_waitcnt lgkmcnt(7)
	v_mfma_f32_16x16x32_bf16 v[76:79], v[172:175], v[92:95], v[76:79]
	ds_read_b128 v[172:175], v116 offset:19456
	v_and_b32_e32 v117, 0xffff0000, v53
	s_lshl_b32 s80, s19, 17
	s_waitcnt lgkmcnt(7)
	v_mfma_f32_16x16x32_bf16 v[76:79], v[176:179], v[72:75], v[76:79]
	ds_read_b128 v[176:179], v116 offset:8192
	s_cmp_lg_u32 s23, 32
	s_mov_b32 s19, s23
	s_waitcnt lgkmcnt(7)
	v_mfma_f32_16x16x32_bf16 v[76:79], v[180:183], v[68:71], v[76:79]
	ds_read_b128 v[180:183], v116 offset:9216
	s_waitcnt lgkmcnt(7)
	v_mfma_f32_16x16x32_bf16 v[80:83], v[184:187], v[88:91], 0
	ds_read_b128 v[184:187], v116 offset:10240
	s_waitcnt lgkmcnt(7)
	v_mfma_f32_16x16x32_bf16 v[80:83], v[188:191], v[100:103], v[80:83]
	ds_read_b128 v[188:191], v116 offset:11264
	s_waitcnt lgkmcnt(7)
	v_mfma_f32_16x16x32_bf16 v[80:83], v[160:163], v[96:99], v[80:83]
	ds_read_b128 v[160:163], v116 offset:20480
	s_waitcnt lgkmcnt(7)
	v_mfma_f32_16x16x32_bf16 v[80:83], v[164:167], v[92:95], v[80:83]
	ds_read_b128 v[164:167], v116 offset:21504
	s_waitcnt lgkmcnt(7)
	v_mfma_f32_16x16x32_bf16 v[80:83], v[168:171], v[72:75], v[80:83]
	ds_read_b128 v[168:171], v116 offset:12288
	s_waitcnt lgkmcnt(7)
	v_mfma_f32_16x16x32_bf16 v[80:83], v[172:175], v[68:71], v[80:83]
	ds_read_b128 v[172:175], v116 offset:13312
	s_waitcnt lgkmcnt(7)
	v_mfma_f32_16x16x32_bf16 v[84:87], v[176:179], v[88:91], 0
	ds_read_b128 v[176:179], v116 offset:14336
	s_waitcnt lgkmcnt(7)
	v_mfma_f32_16x16x32_bf16 v[84:87], v[180:183], v[100:103], v[84:87]
	ds_read_b128 v[180:183], v116 offset:15360
	s_waitcnt lgkmcnt(7)
	v_mfma_f32_16x16x32_bf16 v[84:87], v[184:187], v[96:99], v[84:87]
	ds_read_b128 v[184:187], v116 offset:22528
	s_waitcnt lgkmcnt(7)
	v_mfma_f32_16x16x32_bf16 v[84:87], v[188:191], v[92:95], v[84:87]
	ds_read_b128 v[188:191], v116 offset:23552
	s_waitcnt lgkmcnt(7)
	v_mfma_f32_16x16x32_bf16 v[84:87], v[160:163], v[72:75], v[84:87]
	s_waitcnt lgkmcnt(6)
	v_mfma_f32_16x16x32_bf16 v[84:87], v[164:167], v[68:71], v[84:87]
	ds_read_b128 v[164:167], v116 offset:24576
	s_waitcnt lgkmcnt(6)
	v_mfma_f32_16x16x32_bf16 v[88:91], v[168:171], v[88:91], 0
	ds_read_b128 v[168:171], v116 offset:25600
	s_waitcnt lgkmcnt(6)
	v_mfma_f32_16x16x32_bf16 v[88:91], v[172:175], v[100:103], v[88:91]
	v_lshlrev_b32_e32 v120, 16, v52
	v_and_b32_e32 v121, 0xffff0000, v52
	s_waitcnt lgkmcnt(5)
	v_mfma_f32_16x16x32_bf16 v[88:91], v[176:179], v[96:99], v[88:91]
	ds_read_b128 v[176:179], v116 offset:26624
	v_lshlrev_b32_e32 v100, 16, v54
	v_and_b32_e32 v101, 0xffff0000, v54
	s_waitcnt lgkmcnt(5)
	v_mfma_f32_16x16x32_bf16 v[88:91], v[180:183], v[92:95], v[88:91]
	ds_read_b128 v[180:183], v116 offset:27648
	v_add_u32_e32 v96, s15, v112
	ds_read_b128 v[160:163], v96 offset:57344
	ds_read_b128 v[172:175], v96 offset:57408
	v_and_b32_e32 v97, 0xffff0000, v55
	s_waitcnt lgkmcnt(7)
	v_mfma_f32_16x16x32_bf16 v[88:91], v[184:187], v[72:75], v[88:91]
	ds_read_b128 v[184:187], v96 offset:57472
	s_waitcnt lgkmcnt(7)
	v_mfma_f32_16x16x32_bf16 v[88:91], v[188:191], v[68:71], v[88:91]
	ds_read_b128 v[188:191], v116 offset:28672
	s_waitcnt lgkmcnt(3)
	v_pk_mul_f32 v[44:45], v[44:45], v[160:161]
	v_pk_mul_f32 v[46:47], v[46:47], v[162:163]
	ds_read_b128 v[160:163], v116 offset:29696
	s_nop 0
	v_mfma_f32_16x16x32_bf16 v[44:47], v[164:167], v[72:75], v[44:47]
	ds_read_b128 v[164:167], v96 offset:57536
	v_mfma_f32_16x16x32_bf16 v[44:47], v[168:171], v[68:71], v[44:47]
	ds_read_b128 v[168:171], v116 offset:30720
	s_waitcnt lgkmcnt(5)
	v_pk_mul_f32 v[48:49], v[48:49], v[172:173]
	v_pk_mul_f32 v[50:51], v[50:51], v[174:175]
	ds_read_b128 v[172:175], v116 offset:31744
	s_nop 0
	v_mfma_f32_16x16x32_bf16 v[48:51], v[176:179], v[72:75], v[48:51]
	ds_read_b128 v[176:179], v96 offset:57600
	v_mfma_f32_16x16x32_bf16 v[48:51], v[180:183], v[68:71], v[48:51]
	ds_read_b128 v[180:183], v116 offset:32768
	s_waitcnt lgkmcnt(7)
	v_pk_mul_f32 v[40:41], v[40:41], v[184:185]
	v_pk_mul_f32 v[42:43], v[42:43], v[186:187]
	ds_read_b128 v[184:187], v116 offset:33792
	s_waitcnt lgkmcnt(7)
; #define LAS __attribute__((address_space(3)))
; __device__ __forceinline__ unsigned cvt_pk_bf16(float lo, float hi) { const f32x2 v = {lo, hi}; return __builtin_bit_cast(unsigned, __builtin_convertvector(v, bf16x2_t)); }
; __device__ __forceinline__ float bf_lo(unsigned w) { return __uint_as_float(w << 16); }
; __device__ __forceinline__ float bf_hi(unsigned w) { return __uint_as_float(w & 0xffff0000u); }
; #define LDS_WAIT() asm volatile("s_waitcnt lgkmcnt(0)" ::: "memory")
; template <bool GD>
; __device__ __forceinline__ void chain_wg(CArgs* a, LAS unsigned char* lds, int l, int bh) {
;     ...
; #pragma unroll
;         for (int db = 0; db < 8; ++db) {
;             if (GD) S[db] = S[db] * eg; else S[db] = S[db] * *(const LAS f32x4*)(B + OP_MISC + (16 * db + 4 * fq) * 4);
; #pragma unroll
;             for (int k2 = 0; k2 < 2; ++k2) S[db] = __builtin_amdgcn_mfma_f32_16x16x32_bf16(*(const LAS bf16x8*)(B + (GD ? OG_KDT : OP_KDT) + (db * 2 + k2) * 1024 + lane * 16), Vf[k2], S[db], 0, 0, 0); }
; #pragma unroll
;         for (int tb = 0; tb < 4; ++tb) { const unsigned p01 = cvt_pk_bf16(o[tb][0], o[tb][1]), p23 = cvt_pk_bf16(o[tb][2], o[tb][3]); LAS bf16_t* q = (LAS bf16_t*)(OTW + (16 * tb + 4 * fq) * 32 + fr * 2);
;             q[0] = (bf16_t)(p01 & 0xffffu); q[16] = (bf16_t)(p01 >> 16); q[32] = (bf16_t)(p23 & 0xffffu); q[48] = (bf16_t)(p23 >> 16); }
;         LDS_WAIT();
;         const u32x4 r0 = *(const LAS u32x4*)(OTW + lane * 32), r1 = *(const LAS u32x4*)(OTW + lane * 32 + 16);
;         float ov[16] = {bf_lo(r0.x), bf_hi(r0.x), bf_lo(r0.y), bf_hi(r0.y), bf_lo(r0.z), bf_hi(r0.z), bf_lo(r0.w), bf_hi(r0.w), bf_lo(r1.x), bf_hi(r1.x), bf_lo(r1.y), bf_hi(r1.y), bf_lo(r1.z), bf_hi(r1.z), bf_lo(r1.w), bf_hi(r1.w)};
;         float sq = 0.f;
; #pragma unroll
;         for (int k = 0; k < 16; ++k) sq += ov[k] * ov[k];
;         RED[((c & 1) * 8 + wid) * 64 + lane] = sq;
	v_mfma_f32_16x16x32_bf16 v[40:43], v[188:191], v[72:75], v[40:43]
	ds_read_b128 v[188:191], v96 offset:57664
	s_waitcnt lgkmcnt(7)
	v_mfma_f32_16x16x32_bf16 v[40:43], v[160:163], v[68:71], v[40:43]
	ds_read_b128 v[160:163], v116 offset:34816
	s_waitcnt lgkmcnt(7)
	v_pk_mul_f32 v[36:37], v[36:37], v[164:165]
	v_pk_mul_f32 v[38:39], v[38:39], v[166:167]
	ds_read_b128 v[164:167], v116 offset:35840
	s_waitcnt lgkmcnt(7)
	v_mfma_f32_16x16x32_bf16 v[36:39], v[168:171], v[72:75], v[36:39]
	ds_read_b128 v[168:171], v96 offset:57728
	s_waitcnt lgkmcnt(7)
	v_mfma_f32_16x16x32_bf16 v[36:39], v[172:175], v[68:71], v[36:39]
	ds_read_b128 v[172:175], v116 offset:36864
	s_waitcnt lgkmcnt(7)
	v_pk_mul_f32 v[32:33], v[32:33], v[176:177]
	v_pk_mul_f32 v[34:35], v[34:35], v[178:179]
	ds_read_b128 v[176:179], v116 offset:37888
	s_waitcnt lgkmcnt(7)
	v_mfma_f32_16x16x32_bf16 v[32:35], v[180:183], v[72:75], v[32:35]
	ds_read_b128 v[180:183], v96 offset:57792
	s_waitcnt lgkmcnt(7)
	v_mfma_f32_16x16x32_bf16 v[32:35], v[184:187], v[68:71], v[32:35]
	ds_read_b128 v[184:187], v116 offset:38912
	s_waitcnt lgkmcnt(7)
	v_pk_mul_f32 v[24:25], v[24:25], v[188:189]
	v_pk_mul_f32 v[26:27], v[26:27], v[190:191]
	ds_read_b128 v[188:191], v116 offset:39936
	s_waitcnt lgkmcnt(7)
	v_mfma_f32_16x16x32_bf16 v[24:27], v[160:163], v[72:75], v[24:27]
	s_waitcnt lgkmcnt(6)
	v_mfma_f32_16x16x32_bf16 v[24:27], v[164:167], v[68:71], v[24:27]
	s_waitcnt lgkmcnt(5)
	v_pk_mul_f32 v[20:21], v[20:21], v[168:169]
	v_pk_mul_f32 v[22:23], v[22:23], v[170:171]
	s_waitcnt lgkmcnt(4)
	s_nop 0
	v_mfma_f32_16x16x32_bf16 v[20:23], v[172:175], v[72:75], v[20:23]
	s_waitcnt lgkmcnt(3)
	v_mfma_f32_16x16x32_bf16 v[20:23], v[176:179], v[68:71], v[20:23]
	v_lshlrev_b32_e32 v96, 16, v55
	s_waitcnt lgkmcnt(2)
	v_pk_mul_f32 v[28:29], v[28:29], v[180:181]
	v_pk_mul_f32 v[30:31], v[30:31], v[182:183]
	s_waitcnt lgkmcnt(1)
	s_nop 0
	v_mfma_f32_16x16x32_bf16 v[28:31], v[184:187], v[72:75], v[28:31]
	v_lshlrev_b32_e32 v92, 16, v56
	v_and_b32_e32 v93, 0xffff0000, v56
	s_waitcnt lgkmcnt(0)
	v_mfma_f32_16x16x32_bf16 v[28:31], v[188:191], v[68:71], v[28:31]
	v_cvt_pk_bf16_f32 v68, v76, v77
	v_cvt_pk_bf16_f32 v69, v78, v79
	ds_write_b16 v114, v68
	ds_write_b16_d16_hi v114, v68 offset:32
	ds_write_b16 v114, v69 offset:64
	ds_write_b16_d16_hi v114, v69 offset:96
	v_cvt_pk_bf16_f32 v68, v80, v81
	v_cvt_pk_bf16_f32 v69, v82, v83
	ds_write_b16 v114, v68 offset:512
	ds_write_b16_d16_hi v114, v68 offset:544
	ds_write_b16 v114, v69 offset:576
	ds_write_b16_d16_hi v114, v69 offset:608
	v_cvt_pk_bf16_f32 v68, v84, v85
	v_cvt_pk_bf16_f32 v69, v86, v87
	ds_write_b16 v114, v68 offset:1024
	ds_write_b16_d16_hi v114, v68 offset:1056
	ds_write_b16 v114, v69 offset:1088
	ds_write_b16_d16_hi v114, v69 offset:1120
	v_cvt_pk_bf16_f32 v68, v88, v89
	v_cvt_pk_bf16_f32 v69, v90, v91
	ds_write_b16 v114, v68 offset:1536
	ds_write_b16_d16_hi v114, v68 offset:1568
	ds_write_b16 v114, v69 offset:1600
	ds_write_b16_d16_hi v114, v69 offset:1632
	s_waitcnt lgkmcnt(0)
	ds_read_b128 v[68:71], v115
	ds_read_b128 v[72:75], v115 offset:16
	v_lshlrev_b32_e32 v88, 16, v57
	v_and_b32_e32 v89, 0xffff0000, v57
	v_lshlrev_b32_e32 v80, 16, v59
	s_waitcnt lgkmcnt(0)
	v_lshlrev_b32_e32 v118, 16, v68
	v_and_b32_e32 v119, 0xffff0000, v68
	v_lshlrev_b32_e32 v54, 16, v69
	v_and_b32_e32 v55, 0xffff0000, v69
	v_pk_mul_f32 v[68:69], v[118:119], v[118:119]
	v_pk_mul_f32 v[102:103], v[54:55], v[54:55]
	v_add_f32_e32 v52, v68, v69
	v_lshlrev_b32_e32 v98, 16, v70
	v_and_b32_e32 v99, 0xffff0000, v70
	v_add_f32_e32 v52, v102, v52
	v_lshlrev_b32_e32 v56, 16, v71
	v_and_b32_e32 v57, 0xffff0000, v71
	v_pk_mul_f32 v[70:71], v[98:99], v[98:99]
	v_add_f32_e32 v52, v103, v52
	v_add_f32_e32 v52, v70, v52
	v_pk_mul_f32 v[94:95], v[56:57], v[56:57]
	v_add_f32_e32 v52, v71, v52
	v_lshlrev_b32_e32 v90, 16, v72
	v_and_b32_e32 v91, 0xffff0000, v72
	v_add_f32_e32 v52, v94, v52
	v_and_b32_e32 v81, 0xffff0000, v59
	v_lshlrev_b32_e32 v84, 16, v58
	v_and_b32_e32 v85, 0xffff0000, v58
	v_lshlrev_b32_e32 v58, 16, v73
	v_and_b32_e32 v59, 0xffff0000, v73
	v_pk_mul_f32 v[72:73], v[90:91], v[90:91]
	v_add_f32_e32 v52, v95, v52
	v_add_f32_e32 v52, v72, v52
	v_pk_mul_f32 v[86:87], v[58:59], v[58:59]
	v_add_f32_e32 v52, v73, v52
	v_lshlrev_b32_e32 v82, 16, v74
	v_and_b32_e32 v83, 0xffff0000, v74
	v_add_f32_e32 v52, v86, v52
	v_lshlrev_b32_e32 v76, 16, v75
	v_and_b32_e32 v77, 0xffff0000, v75
	v_pk_mul_f32 v[74:75], v[82:83], v[82:83]
	v_add_f32_e32 v52, v87, v52
	v_add_f32_e32 v52, v74, v52
	v_pk_mul_f32 v[78:79], v[76:77], v[76:77]
	v_add_f32_e32 v52, v75, v52
	v_add_f32_e32 v52, v78, v52
	v_add_f32_e32 v52, v79, v52
	ds_write_b32 v123, v52
	v_lshlrev_b32_e32 v116, 16, v53
	s_waitcnt vmcnt(0)
	s_waitcnt vmcnt(0) lgkmcnt(0)
	s_barrier
; __device__ __forceinline__ unsigned cvt_pk_bf16(float lo, float hi) { const f32x2 v = {lo, hi}; return __builtin_bit_cast(unsigned, __builtin_convertvector(v, bf16x2_t)); }
; __device__ __forceinline__ float bf_lo(unsigned w) { return __uint_as_float(w << 16); }
; __device__ __forceinline__ float bf_hi(unsigned w) { return __uint_as_float(w & 0xffff0000u); }
; #define VM_WAIT() asm volatile("s_waitcnt vmcnt(0)" ::: "memory")
; template <bool GD>
; __device__ __forceinline__ void chain_wg(CArgs* a, LAS unsigned char* lds, int l, int bh) {
;     ...
;         VM_WAIT(); __syncthreads();
;         float tot = 0.f;
; #pragma unroll
;         for (int w2 = 0; w2 < 8; ++w2) tot += RED[((c & 1) * 8 + w2) * 64 + lane];
;         const float rstd = __builtin_amdgcn_rsqf(tot * (1.0f / HD) + EPS);
;         const float gv[16] = {bf_lo(g0.x), bf_hi(g0.x), bf_lo(g0.y), bf_hi(g0.y), bf_lo(g0.z), bf_hi(g0.z), bf_lo(g0.w), bf_hi(g0.w), bf_lo(g1.x), bf_hi(g1.x), bf_lo(g1.y), bf_hi(g1.y), bf_lo(g1.z), bf_hi(g1.z), bf_lo(g1.w), bf_hi(g1.w)};
;         u32x4 y0, y1;
;         y0.x = cvt_pk_bf16(ov[0] * rstd * nwv[0][0] * gv[0], ov[1] * rstd * nwv[0][1] * gv[1]); y0.y = cvt_pk_bf16(ov[2] * rstd * nwv[0][2] * gv[2], ov[3] * rstd * nwv[0][3] * gv[3]);
;         y0.z = cvt_pk_bf16(ov[4] * rstd * nwv[1][0] * gv[4], ov[5] * rstd * nwv[1][1] * gv[5]); y0.w = cvt_pk_bf16(ov[6] * rstd * nwv[1][2] * gv[6], ov[7] * rstd * nwv[1][3] * gv[7]);
;         y1.x = cvt_pk_bf16(ov[8] * rstd * nwv[2][0] * gv[8], ov[9] * rstd * nwv[2][1] * gv[9]); y1.y = cvt_pk_bf16(ov[10] * rstd * nwv[2][2] * gv[10], ov[11] * rstd * nwv[2][3] * gv[11]);
;         y1.z = cvt_pk_bf16(ov[12] * rstd * nwv[3][0] * gv[12], ov[13] * rstd * nwv[3][1] * gv[13]); y1.w = cvt_pk_bf16(ov[14] * rstd * nwv[3][2] * gv[14], ov[15] * rstd * nwv[3][3] * gv[15]);
;         bf16_t* yp = ybase + (size_t)c * 64 * RGW; *(u32x4*)yp = y0; *(u32x4*)(yp + 8) = y1;
;         g0 = ng0; g1 = ng1;
	ds_read2st64_b32 v[52:53], v122 offset1:1
	s_waitcnt lgkmcnt(0)
	v_add_f32_e32 v52, 0, v52
	v_add_f32_e32 v68, v52, v53
	ds_read2st64_b32 v[52:53], v122 offset0:2 offset1:3
	s_waitcnt lgkmcnt(0)
	v_add_f32_e32 v52, v68, v52
	v_add_f32_e32 v68, v52, v53
	ds_read2st64_b32 v[52:53], v122 offset0:4 offset1:5
	s_waitcnt lgkmcnt(0)
	v_add_f32_e32 v52, v68, v52
	v_add_f32_e32 v68, v52, v53
	ds_read2st64_b32 v[52:53], v122 offset0:6 offset1:7
	s_waitcnt lgkmcnt(0)
	v_add_f32_e32 v52, v68, v52
	v_add_f32_e32 v52, v52, v53
	v_fmamk_f32 v52, v52, 0x3c000000, v1
	v_rsq_f32_e32 v68, v52
	s_nop 0
	v_pk_mul_f32 v[52:53], v[68:69], v[118:119] op_sel_hi:[0,1]
	v_pk_mul_f32 v[54:55], v[68:69], v[54:55] op_sel_hi:[0,1]
	v_pk_mul_f32 v[52:53], v[16:17], v[52:53]
	v_pk_mul_f32 v[54:55], v[18:19], v[54:55]
	v_pk_mul_f32 v[52:53], v[52:53], v[120:121]
	v_pk_mul_f32 v[54:55], v[54:55], v[116:117]
	v_cvt_pk_bf16_f32 v52, v52, v53
	v_cvt_pk_bf16_f32 v53, v54, v55
	v_pk_mul_f32 v[54:55], v[68:69], v[98:99] op_sel_hi:[0,1]
	v_pk_mul_f32 v[56:57], v[68:69], v[56:57] op_sel_hi:[0,1]
	v_pk_mul_f32 v[54:55], v[12:13], v[54:55]
	v_pk_mul_f32 v[56:57], v[14:15], v[56:57]
	v_pk_mul_f32 v[54:55], v[54:55], v[100:101]
	v_pk_mul_f32 v[56:57], v[56:57], v[96:97]
	v_cvt_pk_bf16_f32 v54, v54, v55
	v_cvt_pk_bf16_f32 v55, v56, v57
	v_pk_mul_f32 v[56:57], v[68:69], v[90:91] op_sel_hi:[0,1]
	v_pk_mul_f32 v[58:59], v[68:69], v[58:59] op_sel_hi:[0,1]
	v_pk_mul_f32 v[56:57], v[8:9], v[56:57]
	v_pk_mul_f32 v[58:59], v[10:11], v[58:59]
	v_pk_mul_f32 v[56:57], v[56:57], v[92:93]
	v_pk_mul_f32 v[58:59], v[58:59], v[88:89]
	v_cvt_pk_bf16_f32 v56, v56, v57
	v_cvt_pk_bf16_f32 v57, v58, v59
	v_pk_mul_f32 v[58:59], v[68:69], v[82:83] op_sel_hi:[0,1]
	v_pk_mul_f32 v[68:69], v[68:69], v[76:77] op_sel_hi:[0,1]
	v_pk_mul_f32 v[58:59], v[4:5], v[58:59]
	v_pk_mul_f32 v[68:69], v[6:7], v[68:69]
	v_pk_mul_f32 v[58:59], v[58:59], v[84:85]
	v_pk_mul_f32 v[68:69], v[68:69], v[80:81]
	v_cvt_pk_bf16_f32 v58, v58, v59
	v_cvt_pk_bf16_f32 v59, v68, v69
	v_lshl_add_u64 v[68:69], v[108:109], 0, s[80:81]
	global_store_dwordx4 v[68:69], v[52:55], off
	global_store_dwordx4 v[68:69], v[56:59], off offset:16
	s_nop 0
	v_mov_b64_e32 v[52:53], v[64:65]
	v_mov_b64_e32 v[56:57], v[60:61]
	v_mov_b64_e32 v[54:55], v[66:67]
	v_mov_b64_e32 v[58:59], v[62:63]
	s_cbranch_scc0 .LBB0_1150

; #define LAS __attribute__((address_space(3)))
; __device__ __forceinline__ float bf_lo(unsigned w) { return __uint_as_float(w << 16); }
; __device__ __forceinline__ float bf_hi(unsigned w) { return __uint_as_float(w & 0xffff0000u); }
; template <bool GD>
; __device__ __forceinline__ void chain_wg(CArgs* a, LAS unsigned char* lds, int l, int bh) {
;     ...
;         bf16x8 Sf[4];
; #pragma unroll
;         for (int ks = 0; ks < 4; ++ks) Sf[ks] = pack_frag(S[2 * ks], S[2 * ks + 1]);
;         bf16x8 Vf[2];
;         f32x4 o[4];
;         if (GD) {
;             f32x4 vn[4];
; #pragma unroll
;             for (int pr = 0; pr < 2; ++pr) { vn[2 * pr] = (f32x4){bf_lo(un[pr].x), bf_hi(un[pr].x), bf_lo(un[pr].y), bf_hi(un[pr].y)}; vn[2 * pr + 1] = (f32x4){bf_lo(un[pr].z), bf_hi(un[pr].z), bf_lo(un[pr].w), bf_hi(un[pr].w)}; }
; #pragma unroll
;             for (int tb = 0; tb < 4; ++tb)
; #pragma unroll
;                 for (int ks = 0; ks < 4; ++ks) vn[tb] = __builtin_amdgcn_mfma_f32_16x16x32_bf16(*(const LAS bf16x8*)(B + OG_WN + (tb * 4 + ks) * 1024 + lane * 16), Sf[ks], vn[tb], 0, 0, 0);
;             Vf[0] = pack_frag(vn[0], vn[1]); Vf[1] = pack_frag(vn[2], vn[3]);
;         } else {
;             Vf[0] = *(const LAS bf16x8*)(B + OP_VT + (wid * 2 + 0) * 1024 + lane * 16); Vf[1] = *(const LAS bf16x8*)(B + OP_VT + (wid * 2 + 1) * 1024 + lane * 16);
;         }
; #pragma unroll
;         for (int tb = 0; tb < 4; ++tb) { o[tb] = zero4;
; #pragma unroll
;             for (int ks = 0; ks < 4; ++ks) o[tb] = __builtin_amdgcn_mfma_f32_16x16x32_bf16(*(const LAS bf16x8*)(B + (GD ? OG_QG : OP_QG) + (tb * 4 + ks) * 1024 + lane * 16), Sf[ks], o[tb], 0, 0, 0);
; #pragma unroll
;             for (int k2 = 0; k2 < 2; ++k2) o[tb] = __builtin_amdgcn_mfma_f32_16x16x32_bf16(*(const LAS bf16x8*)(B + (GD ? OG_QK : OP_A) + (tb * 2 + k2) * 1024 + lane * 16), Vf[k2], o[tb], 0, 0, 0); }
.LBB0_1158:
	s_and_b32 s15, s22, 1
	s_mul_i32 s16, s15, 0xe400
	s_add_i32 s16, s16, 0
	v_add_u32_e32 v125, s16, v112
	ds_read_b128 v[160:163], v125
	ds_read_b128 v[164:167], v125 offset:1024
	ds_read_b128 v[168:171], v125 offset:2048
	ds_read_b128 v[172:175], v125 offset:3072
	ds_read_b128 v[176:179], v125 offset:4096
	ds_read_b128 v[180:183], v125 offset:5120
	ds_read_b128 v[184:187], v125 offset:6144
	ds_read_b128 v[188:191], v125 offset:7168
	v_cvt_pk_bf16_f32 v76, v44, v45
	v_cvt_pk_bf16_f32 v77, v46, v47
	v_cvt_pk_bf16_f32 v78, v48, v49
	v_cvt_pk_bf16_f32 v79, v50, v51
	v_lshlrev_b32_e32 v100, 16, v96
	v_and_b32_e32 v101, 0xffff0000, v96
	v_lshlrev_b32_e32 v102, 16, v97
	v_and_b32_e32 v103, 0xffff0000, v97
	v_cvt_pk_bf16_f32 v80, v40, v41
	v_cvt_pk_bf16_f32 v81, v42, v43
	s_waitcnt lgkmcnt(7)
	v_mfma_f32_16x16x32_bf16 v[100:103], v[160:163], v[76:79], v[100:103]
	ds_read_b128 v[160:163], v125 offset:8192
	v_cvt_pk_bf16_f32 v82, v36, v37
	v_cvt_pk_bf16_f32 v83, v38, v39
	v_cvt_pk_bf16_f32 v84, v32, v33
	v_cvt_pk_bf16_f32 v85, v34, v35
	v_cvt_pk_bf16_f32 v86, v28, v29
	s_waitcnt lgkmcnt(7)
	v_mfma_f32_16x16x32_bf16 v[100:103], v[164:167], v[80:83], v[100:103]
	ds_read_b128 v[164:167], v125 offset:9216
	v_cvt_pk_bf16_f32 v87, v30, v31
	v_cvt_pk_bf16_f32 v88, v24, v25
	v_cvt_pk_bf16_f32 v89, v26, v27
	v_cvt_pk_bf16_f32 v90, v20, v21
	s_waitcnt lgkmcnt(7)
	v_mfma_f32_16x16x32_bf16 v[100:103], v[168:171], v[84:87], v[100:103]
	ds_read_b128 v[168:171], v125 offset:10240
	v_cvt_pk_bf16_f32 v91, v22, v23
	v_lshlrev_b32_e32 v104, 16, v98
	v_and_b32_e32 v105, 0xffff0000, v98
	s_waitcnt lgkmcnt(7)
	v_mfma_f32_16x16x32_bf16 v[100:103], v[172:175], v[88:91], v[100:103]
	ds_read_b128 v[172:175], v125 offset:11264
	v_lshlrev_b32_e32 v106, 16, v99
	v_and_b32_e32 v107, 0xffff0000, v99
	v_lshlrev_b32_e32 v96, 16, v92
	v_and_b32_e32 v97, 0xffff0000, v92
	s_waitcnt lgkmcnt(7)
	v_mfma_f32_16x16x32_bf16 v[104:107], v[176:179], v[76:79], v[104:107]
	ds_read_b128 v[176:179], v125 offset:12288
	v_lshlrev_b32_e32 v98, 16, v93
	v_and_b32_e32 v99, 0xffff0000, v93
	s_waitcnt lgkmcnt(7)
	v_mfma_f32_16x16x32_bf16 v[104:107], v[180:183], v[80:83], v[104:107]
	ds_read_b128 v[180:183], v125 offset:13312
	v_lshlrev_b32_e32 v92, 16, v94
	v_and_b32_e32 v93, 0xffff0000, v94
	s_waitcnt lgkmcnt(7)
	v_mfma_f32_16x16x32_bf16 v[104:107], v[184:187], v[84:87], v[104:107]
	ds_read_b128 v[184:187], v125 offset:14336
	v_lshlrev_b32_e32 v94, 16, v95
	v_and_b32_e32 v95, 0xffff0000, v95
	s_waitcnt lgkmcnt(7)
	v_mfma_f32_16x16x32_bf16 v[104:107], v[188:191], v[88:91], v[104:107]
	ds_read_b128 v[188:191], v125 offset:15360
	v_lshlrev_b32_e32 v130, 16, v52
	v_and_b32_e32 v131, 0xffff0000, v52
	s_waitcnt lgkmcnt(7)
	v_mfma_f32_16x16x32_bf16 v[96:99], v[160:163], v[76:79], v[96:99]
	ds_read_b128 v[160:163], v125 offset:16384
	s_lshl_b32 s80, s22, 17
	s_cmp_lg_u32 s14, 32
	s_waitcnt lgkmcnt(7)
	v_mfma_f32_16x16x32_bf16 v[96:99], v[164:167], v[80:83], v[96:99]
	ds_read_b128 v[164:167], v125 offset:17408
	s_mov_b32 s22, s14
	s_waitcnt lgkmcnt(7)
	v_mfma_f32_16x16x32_bf16 v[96:99], v[168:171], v[84:87], v[96:99]
	ds_read_b128 v[168:171], v125 offset:18432
	s_waitcnt lgkmcnt(7)
	v_mfma_f32_16x16x32_bf16 v[108:111], v[172:175], v[88:91], v[96:99]
	ds_read_b128 v[172:175], v125 offset:19456
	s_nop 4
	s_waitcnt lgkmcnt(7)
	v_mfma_f32_16x16x32_bf16 v[92:95], v[176:179], v[76:79], v[92:95]
	ds_read_b128 v[176:179], v125 offset:32768
	s_waitcnt lgkmcnt(7)
	v_mfma_f32_16x16x32_bf16 v[92:95], v[180:183], v[80:83], v[92:95]
	ds_read_b128 v[180:183], v125 offset:33792
	s_waitcnt lgkmcnt(7)
	v_mfma_f32_16x16x32_bf16 v[92:95], v[184:187], v[84:87], v[92:95]
	ds_read_b128 v[184:187], v125 offset:20480
	s_waitcnt lgkmcnt(7)
	v_mfma_f32_16x16x32_bf16 v[126:129], v[188:191], v[88:91], v[92:95]
	ds_read_b128 v[188:191], v125 offset:21504
	v_cvt_pk_bf16_f32 v96, v100, v101
	v_cvt_pk_bf16_f32 v97, v102, v103
	v_cvt_pk_bf16_f32 v98, v104, v105
	v_cvt_pk_bf16_f32 v99, v106, v107
	s_waitcnt lgkmcnt(7)
	v_mfma_f32_16x16x32_bf16 v[100:103], v[160:163], v[76:79], 0
	ds_read_b128 v[160:163], v125 offset:22528
	v_cvt_pk_bf16_f32 v92, v108, v109
	v_cvt_pk_bf16_f32 v93, v110, v111
	s_waitcnt lgkmcnt(7)
	v_mfma_f32_16x16x32_bf16 v[100:103], v[164:167], v[80:83], v[100:103]
	ds_read_b128 v[164:167], v125 offset:23552
	v_cvt_pk_bf16_f32 v94, v126, v127
	v_cvt_pk_bf16_f32 v95, v128, v129
	s_waitcnt lgkmcnt(7)
	v_mfma_f32_16x16x32_bf16 v[100:103], v[168:171], v[84:87], v[100:103]
	ds_read_b128 v[168:171], v125 offset:34816
	s_waitcnt lgkmcnt(7)
	v_mfma_f32_16x16x32_bf16 v[100:103], v[172:175], v[88:91], v[100:103]
	ds_read_b128 v[172:175], v125 offset:35840
	s_waitcnt lgkmcnt(7)
	v_mfma_f32_16x16x32_bf16 v[100:103], v[176:179], v[96:99], v[100:103]
	ds_read_b128 v[176:179], v125 offset:24576
	s_waitcnt lgkmcnt(7)
	v_mfma_f32_16x16x32_bf16 v[100:103], v[180:183], v[92:95], v[100:103]
	ds_read_b128 v[180:183], v125 offset:25600
	s_waitcnt lgkmcnt(7)
	v_mfma_f32_16x16x32_bf16 v[104:107], v[184:187], v[76:79], 0
	ds_read_b128 v[184:187], v125 offset:26624
	s_waitcnt lgkmcnt(7)
	v_mfma_f32_16x16x32_bf16 v[104:107], v[188:191], v[80:83], v[104:107]
	ds_read_b128 v[188:191], v125 offset:27648
	s_waitcnt lgkmcnt(7)
	v_mfma_f32_16x16x32_bf16 v[104:107], v[160:163], v[84:87], v[104:107]
	ds_read_b128 v[160:163], v125 offset:36864
	s_waitcnt lgkmcnt(7)
	v_mfma_f32_16x16x32_bf16 v[104:107], v[164:167], v[88:91], v[104:107]
	ds_read_b128 v[164:167], v125 offset:37888
	s_waitcnt lgkmcnt(7)
	v_mfma_f32_16x16x32_bf16 v[104:107], v[168:171], v[96:99], v[104:107]
	ds_read_b128 v[168:171], v125 offset:28672
	s_waitcnt lgkmcnt(7)
; #define LAS __attribute__((address_space(3)))
; template <bool GD>
; __device__ __forceinline__ void chain_wg(CArgs* a, LAS unsigned char* lds, int l, int bh) {
;     ...
;             for (int ks = 0; ks < 4; ++ks) o[tb] = __builtin_amdgcn_mfma_f32_16x16x32_bf16(*(const LAS bf16x8*)(B + (GD ? OG_QG : OP_QG) + (tb * 4 + ks) * 1024 + lane * 16), Sf[ks], o[tb], 0, 0, 0);
; #pragma unroll
;             for (int k2 = 0; k2 < 2; ++k2) o[tb] = __builtin_amdgcn_mfma_f32_16x16x32_bf16(*(const LAS bf16x8*)(B + (GD ? OG_QK : OP_A) + (tb * 2 + k2) * 1024 + lane * 16), Vf[k2], o[tb], 0, 0, 0); }
;         const float eg = GD ? *(const LAS float*)(B + OP_MISC) : 0.f;
; #pragma unroll
;         for (int db = 0; db < 8; ++db) {
;             if (GD) S[db] = S[db] * eg; else S[db] = S[db] * *(const LAS f32x4*)(B + OP_MISC + (16 * db + 4 * fq) * 4);
; #pragma unroll
;             for (int k2 = 0; k2 < 2; ++k2) S[db] = __builtin_amdgcn_mfma_f32_16x16x32_bf16(*(const LAS bf16x8*)(B + (GD ? OG_KDT : OP_KDT) + (db * 2 + k2) * 1024 + lane * 16), Vf[k2], S[db], 0, 0, 0); }
	v_mfma_f32_16x16x32_bf16 v[104:107], v[172:175], v[92:95], v[104:107]
	ds_read_b128 v[172:175], v125 offset:29696
	s_waitcnt lgkmcnt(7)
	v_mfma_f32_16x16x32_bf16 v[108:111], v[176:179], v[76:79], 0
	ds_read_b128 v[176:179], v125 offset:30720
	s_waitcnt lgkmcnt(7)
	v_mfma_f32_16x16x32_bf16 v[108:111], v[180:183], v[80:83], v[108:111]
	ds_read_b128 v[180:183], v125 offset:31744
	s_waitcnt lgkmcnt(7)
	v_mfma_f32_16x16x32_bf16 v[108:111], v[184:187], v[84:87], v[108:111]
	ds_read_b128 v[184:187], v125 offset:38912
	s_waitcnt lgkmcnt(7)
	v_mfma_f32_16x16x32_bf16 v[108:111], v[188:191], v[88:91], v[108:111]
	ds_read_b128 v[188:191], v125 offset:39936
	s_waitcnt lgkmcnt(7)
	v_mfma_f32_16x16x32_bf16 v[108:111], v[160:163], v[96:99], v[108:111]
	ds_read_b128 v[160:163], v125 offset:40960
	s_waitcnt lgkmcnt(7)
	v_mfma_f32_16x16x32_bf16 v[108:111], v[164:167], v[92:95], v[108:111]
	ds_read_b128 v[164:167], v125 offset:41984
	s_waitcnt lgkmcnt(7)
	v_mfma_f32_16x16x32_bf16 v[76:79], v[168:171], v[76:79], 0
	ds_read_b128 v[168:171], v125 offset:43008
	s_waitcnt lgkmcnt(7)
	v_mfma_f32_16x16x32_bf16 v[76:79], v[172:175], v[80:83], v[76:79]
	ds_read_b128 v[172:175], v125 offset:44032
	v_lshlrev_b32_e32 v126, 16, v53
	v_and_b32_e32 v127, 0xffff0000, v53
	s_waitcnt lgkmcnt(7)
	v_mfma_f32_16x16x32_bf16 v[76:79], v[176:179], v[84:87], v[76:79]
	ds_read_b128 v[176:179], v125 offset:45056
	s_waitcnt lgkmcnt(7)
	v_mfma_f32_16x16x32_bf16 v[76:79], v[180:183], v[88:91], v[76:79]
	ds_read_b128 v[180:183], v125 offset:46080
	v_lshlrev_b32_e32 v88, 16, v59
	v_and_b32_e32 v89, 0xffff0000, v59
	s_waitcnt lgkmcnt(7)
	v_mfma_f32_16x16x32_bf16 v[76:79], v[184:187], v[96:99], v[76:79]
	ds_read_b128 v[184:187], v125 offset:47104
	s_waitcnt lgkmcnt(7)
	v_mfma_f32_16x16x32_bf16 v[76:79], v[188:191], v[92:95], v[76:79]
	ds_read_b128 v[188:191], v125 offset:48128
	v_mov_b32_e32 v80, s16
	ds_read_b32 v84, v80 offset:57344
	s_nop 4
	v_cvt_pk_bf16_f32 v76, v76, v77
	v_cvt_pk_bf16_f32 v77, v78, v79
	s_waitcnt lgkmcnt(0)
	v_pk_mul_f32 v[46:47], v[46:47], v[84:85] op_sel_hi:[1,0]
	v_pk_mul_f32 v[44:45], v[44:45], v[84:85] op_sel_hi:[1,0]
	v_pk_mul_f32 v[50:51], v[50:51], v[84:85] op_sel_hi:[1,0]
	v_pk_mul_f32 v[48:49], v[48:49], v[84:85] op_sel_hi:[1,0]
	v_mfma_f32_16x16x32_bf16 v[44:47], v[160:163], v[96:99], v[44:47]
	ds_read_b128 v[160:163], v125 offset:49152
	v_pk_mul_f32 v[42:43], v[42:43], v[84:85] op_sel_hi:[1,0]
	v_pk_mul_f32 v[40:41], v[40:41], v[84:85] op_sel_hi:[1,0]
	v_mfma_f32_16x16x32_bf16 v[44:47], v[164:167], v[92:95], v[44:47]
	ds_read_b128 v[164:167], v125 offset:50176
	v_pk_mul_f32 v[38:39], v[38:39], v[84:85] op_sel_hi:[1,0]
	v_pk_mul_f32 v[36:37], v[36:37], v[84:85] op_sel_hi:[1,0]
	v_mfma_f32_16x16x32_bf16 v[48:51], v[168:171], v[96:99], v[48:51]
	ds_read_b128 v[168:171], v125 offset:51200
	v_pk_mul_f32 v[34:35], v[34:35], v[84:85] op_sel_hi:[1,0]
	v_pk_mul_f32 v[32:33], v[32:33], v[84:85] op_sel_hi:[1,0]
	v_mfma_f32_16x16x32_bf16 v[48:51], v[172:175], v[92:95], v[48:51]
	ds_read_b128 v[172:175], v125 offset:52224
	v_pk_mul_f32 v[30:31], v[30:31], v[84:85] op_sel_hi:[1,0]
	v_pk_mul_f32 v[28:29], v[28:29], v[84:85] op_sel_hi:[1,0]
	v_mfma_f32_16x16x32_bf16 v[40:43], v[176:179], v[96:99], v[40:43]
	ds_read_b128 v[176:179], v125 offset:53248
	v_pk_mul_f32 v[26:27], v[26:27], v[84:85] op_sel_hi:[1,0]
	v_pk_mul_f32 v[24:25], v[24:25], v[84:85] op_sel_hi:[1,0]
	v_mfma_f32_16x16x32_bf16 v[40:43], v[180:183], v[92:95], v[40:43]
	ds_read_b128 v[180:183], v125 offset:54272
	v_pk_mul_f32 v[22:23], v[22:23], v[84:85] op_sel_hi:[1,0]
	v_pk_mul_f32 v[20:21], v[20:21], v[84:85] op_sel_hi:[1,0]
	v_mfma_f32_16x16x32_bf16 v[36:39], v[184:187], v[96:99], v[36:39]
	ds_read_b128 v[184:187], v125 offset:55296
	v_mfma_f32_16x16x32_bf16 v[36:39], v[188:191], v[92:95], v[36:39]
	ds_read_b128 v[188:191], v125 offset:56320
	s_waitcnt lgkmcnt(7)
	v_mfma_f32_16x16x32_bf16 v[32:35], v[160:163], v[96:99], v[32:35]
	s_waitcnt lgkmcnt(6)
	v_mfma_f32_16x16x32_bf16 v[32:35], v[164:167], v[92:95], v[32:35]
	s_waitcnt lgkmcnt(5)
	v_mfma_f32_16x16x32_bf16 v[28:31], v[168:171], v[96:99], v[28:31]
	s_waitcnt lgkmcnt(4)
	v_mfma_f32_16x16x32_bf16 v[28:31], v[172:175], v[92:95], v[28:31]
	s_waitcnt lgkmcnt(3)
	v_mfma_f32_16x16x32_bf16 v[24:27], v[176:179], v[96:99], v[24:27]
	s_waitcnt lgkmcnt(2)
	v_mfma_f32_16x16x32_bf16 v[24:27], v[180:183], v[92:95], v[24:27]
	s_waitcnt lgkmcnt(1)
	v_mfma_f32_16x16x32_bf16 v[20:23], v[184:187], v[96:99], v[20:23]
	v_lshlrev_b32_e32 v96, 16, v57
	v_and_b32_e32 v97, 0xffff0000, v57
	s_waitcnt lgkmcnt(0)
; #define LAS __attribute__((address_space(3)))
; #define LDS_WAIT() asm volatile("s_waitcnt lgkmcnt(0)" ::: "memory")
; template <bool GD>
; __device__ __forceinline__ void chain_wg(CArgs* a, LAS unsigned char* lds, int l, int bh) {
;     ...
;             for (int k2 = 0; k2 < 2; ++k2) S[db] = __builtin_amdgcn_mfma_f32_16x16x32_bf16(*(const LAS bf16x8*)(B + (GD ? OG_KDT : OP_KDT) + (db * 2 + k2) * 1024 + lane * 16), Vf[k2], S[db], 0, 0, 0); }
; #pragma unroll
;         for (int tb = 0; tb < 4; ++tb) { const unsigned p01 = cvt_pk_bf16(o[tb][0], o[tb][1]), p23 = cvt_pk_bf16(o[tb][2], o[tb][3]); LAS bf16_t* q = (LAS bf16_t*)(OTW + (16 * tb + 4 * fq) * 32 + fr * 2);
;             q[0] = (bf16_t)(p01 & 0xffffu); q[16] = (bf16_t)(p01 >> 16); q[32] = (bf16_t)(p23 & 0xffffu); q[48] = (bf16_t)(p23 >> 16); }
;         LDS_WAIT();
;         const u32x4 r0 = *(const LAS u32x4*)(OTW + lane * 32), r1 = *(const LAS u32x4*)(OTW + lane * 32 + 16);
;         float ov[16] = {bf_lo(r0.x), bf_hi(r0.x), bf_lo(r0.y), bf_hi(r0.y), bf_lo(r0.z), bf_hi(r0.z), bf_lo(r0.w), bf_hi(r0.w), bf_lo(r1.x), bf_hi(r1.x), bf_lo(r1.y), bf_hi(r1.y), bf_lo(r1.z), bf_hi(r1.z), bf_lo(r1.w), bf_hi(r1.w)};
;         float sq = 0.f;
; #pragma unroll
;         for (int k = 0; k < 16; ++k) sq += ov[k] * ov[k];
;         RED[((c & 1) * 8 + wid) * 64 + lane] = sq;
;         VM_WAIT(); __syncthreads();
;         float tot = 0.f;
; #pragma unroll
;         for (int w2 = 0; w2 < 8; ++w2) tot += RED[((c & 1) * 8 + w2) * 64 + lane];
;         const float rstd = __builtin_amdgcn_rsqf(tot * (1.0f / HD) + EPS);
;         const float gv[16] = {bf_lo(g0.x), bf_hi(g0.x), bf_lo(g0.y), bf_hi(g0.y), bf_lo(g0.z), bf_hi(g0.z), bf_lo(g0.w), bf_hi(g0.w), bf_lo(g1.x), bf_hi(g1.x), bf_lo(g1.y), bf_hi(g1.y), bf_lo(g1.z), bf_hi(g1.z), bf_lo(g1.w), bf_hi(g1.w)};
;         u32x4 y0, y1;
;         y0.x = cvt_pk_bf16(ov[0] * rstd * nwv[0][0] * gv[0], ov[1] * rstd * nwv[0][1] * gv[1]); y0.y = cvt_pk_bf16(ov[2] * rstd * nwv[0][2] * gv[2], ov[3] * rstd * nwv[0][3] * gv[3]);
;         y0.z = cvt_pk_bf16(ov[4] * rstd * nwv[1][0] * gv[4], ov[5] * rstd * nwv[1][1] * gv[5]); y0.w = cvt_pk_bf16(ov[6] * rstd * nwv[1][2] * gv[6], ov[7] * rstd * nwv[1][3] * gv[7]);
;         y1.x = cvt_pk_bf16(ov[8] * rstd * nwv[2][0] * gv[8], ov[9] * rstd * nwv[2][1] * gv[9]); y1.y = cvt_pk_bf16(ov[10] * rstd * nwv[2][2] * gv[10], ov[11] * rstd * nwv[2][3] * gv[11]);
	v_mfma_f32_16x16x32_bf16 v[20:23], v[188:191], v[92:95], v[20:23]
	v_cvt_pk_bf16_f32 v80, v100, v101
	v_cvt_pk_bf16_f32 v81, v102, v103
	ds_write_b16 v123, v80
	ds_write_b16_d16_hi v123, v80 offset:32
	ds_write_b16 v123, v81 offset:64
	ds_write_b16_d16_hi v123, v81 offset:96
	v_cvt_pk_bf16_f32 v80, v104, v105
	v_cvt_pk_bf16_f32 v81, v106, v107
	ds_write_b16 v123, v80 offset:512
	ds_write_b16_d16_hi v123, v80 offset:544
	ds_write_b16 v123, v81 offset:576
	ds_write_b16_d16_hi v123, v81 offset:608
	v_cvt_pk_bf16_f32 v80, v108, v109
	v_cvt_pk_bf16_f32 v81, v110, v111
	ds_write_b16 v123, v80 offset:1024
	ds_write_b16_d16_hi v123, v80 offset:1056
	ds_write_b16 v123, v81 offset:1088
	ds_write_b16_d16_hi v123, v81 offset:1120
	ds_write_b16 v123, v76 offset:1536
	ds_write_b16_d16_hi v123, v76 offset:1568
	ds_write_b16 v123, v77 offset:1600
	ds_write_b16_d16_hi v123, v77 offset:1632
	s_waitcnt lgkmcnt(0)
	ds_read_b128 v[76:79], v124
	ds_read_b128 v[80:83], v124 offset:16
	v_lshlrev_b32_e32 v104, 16, v55
	v_and_b32_e32 v105, 0xffff0000, v55
	v_lshlrev_b32_e32 v108, 16, v54
	s_waitcnt lgkmcnt(0)
	v_lshlrev_b32_e32 v128, 16, v76
	v_and_b32_e32 v129, 0xffff0000, v76
	v_and_b32_e32 v109, 0xffff0000, v54
	v_lshlrev_b32_e32 v54, 16, v77
	v_and_b32_e32 v55, 0xffff0000, v77
	v_pk_mul_f32 v[76:77], v[128:129], v[128:129]
	v_pk_mul_f32 v[110:111], v[54:55], v[54:55]
	v_add_f32_e32 v52, v76, v77
	v_lshlrev_b32_e32 v106, 16, v78
	v_and_b32_e32 v107, 0xffff0000, v78
	v_add_f32_e32 v52, v110, v52
	v_lshlrev_b32_e32 v100, 16, v56
	v_and_b32_e32 v101, 0xffff0000, v56
	v_lshlrev_b32_e32 v56, 16, v79
	v_and_b32_e32 v57, 0xffff0000, v79
	v_pk_mul_f32 v[78:79], v[106:107], v[106:107]
	v_add_f32_e32 v52, v111, v52
	v_add_f32_e32 v52, v78, v52
	v_pk_mul_f32 v[102:103], v[56:57], v[56:57]
	v_add_f32_e32 v52, v79, v52
	v_lshlrev_b32_e32 v98, 16, v80
	v_and_b32_e32 v99, 0xffff0000, v80
	v_add_f32_e32 v52, v102, v52
	v_lshlrev_b32_e32 v92, 16, v58
	v_and_b32_e32 v93, 0xffff0000, v58
	v_lshlrev_b32_e32 v58, 16, v81
	v_and_b32_e32 v59, 0xffff0000, v81
	v_pk_mul_f32 v[80:81], v[98:99], v[98:99]
	v_add_f32_e32 v52, v103, v52
	v_add_f32_e32 v52, v80, v52
	v_pk_mul_f32 v[94:95], v[58:59], v[58:59]
	v_add_f32_e32 v52, v81, v52
	v_lshlrev_b32_e32 v90, 16, v82
	v_and_b32_e32 v91, 0xffff0000, v82
	v_add_f32_e32 v52, v94, v52
	v_lshlrev_b32_e32 v84, 16, v83
	v_and_b32_e32 v85, 0xffff0000, v83
	v_pk_mul_f32 v[82:83], v[90:91], v[90:91]
	v_add_f32_e32 v52, v95, v52
	v_add_f32_e32 v52, v82, v52
	v_pk_mul_f32 v[86:87], v[84:85], v[84:85]
	v_add_f32_e32 v52, v83, v52
	v_lshl_add_u32 v125, s15, 11, v113
	v_add_f32_e32 v52, v86, v52
	v_add_u32_e32 v132, s23, v125
	v_add_f32_e32 v52, v87, v52
	ds_write_b32 v132, v52
	s_waitcnt vmcnt(0)
	s_waitcnt vmcnt(0) lgkmcnt(0)
	s_barrier
	ds_read2st64_b32 v[52:53], v125 offset1:1
	s_waitcnt lgkmcnt(0)
	v_add_f32_e32 v52, 0, v52
	v_add_f32_e32 v76, v52, v53
	ds_read2st64_b32 v[52:53], v125 offset0:2 offset1:3
	s_waitcnt lgkmcnt(0)
	v_add_f32_e32 v52, v76, v52
	v_add_f32_e32 v76, v52, v53
	ds_read2st64_b32 v[52:53], v125 offset0:4 offset1:5
	s_waitcnt lgkmcnt(0)
	v_add_f32_e32 v52, v76, v52
	v_add_f32_e32 v76, v52, v53
	ds_read2st64_b32 v[52:53], v125 offset0:6 offset1:7
	s_waitcnt lgkmcnt(0)
	v_add_f32_e32 v52, v76, v52
	v_add_f32_e32 v52, v52, v53
	v_fmamk_f32 v52, v52, 0x3c000000, v1
	v_rsq_f32_e32 v76, v52
	s_nop 0
	v_pk_mul_f32 v[52:53], v[76:77], v[128:129] op_sel_hi:[0,1]
	v_pk_mul_f32 v[54:55], v[76:77], v[54:55] op_sel_hi:[0,1]
	v_pk_mul_f32 v[52:53], v[16:17], v[52:53]
	v_pk_mul_f32 v[54:55], v[18:19], v[54:55]
	v_pk_mul_f32 v[52:53], v[52:53], v[130:131]
	v_pk_mul_f32 v[54:55], v[54:55], v[126:127]
	v_cvt_pk_bf16_f32 v52, v52, v53
	v_cvt_pk_bf16_f32 v53, v54, v55
	v_pk_mul_f32 v[54:55], v[76:77], v[106:107] op_sel_hi:[0,1]
	v_pk_mul_f32 v[56:57], v[76:77], v[56:57] op_sel_hi:[0,1]
	v_pk_mul_f32 v[54:55], v[12:13], v[54:55]
	v_pk_mul_f32 v[56:57], v[14:15], v[56:57]
	v_pk_mul_f32 v[54:55], v[54:55], v[108:109]
	v_pk_mul_f32 v[56:57], v[56:57], v[104:105]
	v_cvt_pk_bf16_f32 v54, v54, v55
	v_cvt_pk_bf16_f32 v55, v56, v57
	v_pk_mul_f32 v[56:57], v[76:77], v[98:99] op_sel_hi:[0,1]
	v_pk_mul_f32 v[58:59], v[76:77], v[58:59] op_sel_hi:[0,1]
	v_pk_mul_f32 v[56:57], v[8:9], v[56:57]
	v_pk_mul_f32 v[58:59], v[10:11], v[58:59]
	v_pk_mul_f32 v[56:57], v[56:57], v[100:101]
	v_pk_mul_f32 v[58:59], v[58:59], v[96:97]
	v_cvt_pk_bf16_f32 v56, v56, v57
	v_cvt_pk_bf16_f32 v57, v58, v59
	v_pk_mul_f32 v[58:59], v[76:77], v[90:91] op_sel_hi:[0,1]
	v_pk_mul_f32 v[76:77], v[76:77], v[84:85] op_sel_hi:[0,1]
	v_pk_mul_f32 v[58:59], v[4:5], v[58:59]
	v_pk_mul_f32 v[76:77], v[6:7], v[76:77]
	v_pk_mul_f32 v[58:59], v[58:59], v[92:93]
	v_pk_mul_f32 v[76:77], v[76:77], v[88:89]
	v_cvt_pk_bf16_f32 v58, v58, v59
	v_cvt_pk_bf16_f32 v59, v76, v77
	v_lshl_add_u64 v[76:77], v[116:117], 0, s[80:81]
	global_store_dwordx4 v[76:77], v[52:55], off
	global_store_dwordx4 v[76:77], v[56:59], off offset:16
	v_mov_b64_e32 v[94:95], v[74:75]
	v_mov_b64_e32 v[98:99], v[70:71]
	v_mov_b64_e32 v[52:53], v[64:65]
	v_mov_b64_e32 v[56:57], v[60:61]
	v_mov_b64_e32 v[92:93], v[72:73]
	v_mov_b64_e32 v[96:97], v[68:69]
	v_mov_b64_e32 v[54:55], v[66:67]
	v_mov_b64_e32 v[58:59], v[62:63]
	s_cbranch_scc0 .LBB0_1165
